# NSA attention block loops: running-max reduction across lane groups via v_permlane16/32_swap instead of ds_swizzle + ds_bpermute round trips
# speedup vs baseline: 1.0057x; 1.0005x over previous
.LBB0_161:
	s_cmp_lg_u32 s0, s22
	s_cselect_b64 s[42:43], -1, 0
	s_lshl_b32 s1, s0, 6
	s_mul_i32 s23, s18, 0x2400
	v_subrev_u32_e32 v16, s1, v162
	s_mov_b64 s[6:7], -1
	s_lshl_b32 s25, 1, s0
	v_add_u32_e32 v122, s23, v197
	v_add_u32_e32 v17, v16, v140
	s_and_b64 vcc, exec, s[42:43]
	s_cbranch_vccz .LBB0_163
	v_add_u32_e32 v10, v122, v199
	ds_read_b128 v[0:3], v10
	ds_read_b128 v[4:7], v10 offset:64
	v_cvt_f32_i32_e32 v8, v17
	v_and_b32_e32 v9, s25, v161
	v_cmp_ne_u32_e32 vcc, 0, v9
	s_waitcnt lgkmcnt(1)
	v_mfma_f32_16x16x32_bf16 v[0:3], v[0:3], v[34:37], 0
	s_waitcnt lgkmcnt(0)
	v_mfma_f32_16x16x32_bf16 v[0:3], v[4:7], v[38:41], v[0:3]
	ds_read_b128 v[4:7], v10 offset:2368
	s_nop 6
	v_fmamk_f32 v11, v0, 0x3e38aa3b, v137
	v_fmamk_f32 v12, v1, 0x3e38aa3b, v145
	v_max3_f32 v0, v11, s85, v12
	v_fmamk_f32 v13, v2, 0x3e38aa3b, v200
	v_fmamk_f32 v14, v3, 0x3e38aa3b, v201
	v_max3_f32 v15, v0, v13, v14
	ds_read_b128 v[0:3], v10 offset:2304
	s_waitcnt lgkmcnt(0)
	v_mfma_f32_16x16x32_bf16 v[0:3], v[0:3], v[34:37], 0
	v_mfma_f32_16x16x32_bf16 v[0:3], v[4:7], v[38:41], v[0:3]
	ds_read_b128 v[4:7], v10 offset:4672
	s_nop 6
	v_fmamk_f32 v18, v0, 0x3e38aa3b, v202
	v_fmamk_f32 v19, v1, 0x3e38aa3b, v203
	v_max3_f32 v0, v15, v18, v19
	v_fmamk_f32 v15, v2, 0x3e38aa3b, v204
	v_fmamk_f32 v20, v3, 0x3e38aa3b, v205
	v_max3_f32 v21, v0, v15, v20
	ds_read_b128 v[0:3], v10 offset:4608
	s_waitcnt lgkmcnt(0)
	v_mfma_f32_16x16x32_bf16 v[0:3], v[0:3], v[34:37], 0
	v_mfma_f32_16x16x32_bf16 v[0:3], v[4:7], v[38:41], v[0:3]
	ds_read_b128 v[4:7], v10 offset:6976
	s_nop 6
	v_fmamk_f32 v22, v0, 0x3e38aa3b, v206
	v_fmamk_f32 v23, v1, 0x3e38aa3b, v207
	v_max3_f32 v0, v21, v22, v23
	v_fmamk_f32 v21, v2, 0x3e38aa3b, v208
	v_fmamk_f32 v24, v3, 0x3e38aa3b, v209
	v_max3_f32 v25, v0, v21, v24
	ds_read_b128 v[0:3], v10 offset:6912
	s_waitcnt lgkmcnt(0)
	v_mfma_f32_16x16x32_bf16 v[0:3], v[0:3], v[34:37], 0
	v_mfma_f32_16x16x32_bf16 v[0:3], v[4:7], v[38:41], v[0:3]
	s_nop 7
	v_fmamk_f32 v26, v0, 0x3e38aa3b, v210
	v_fmamk_f32 v27, v1, 0x3e38aa3b, v211
	v_max3_f32 v0, v25, v26, v27
	v_fmamk_f32 v25, v2, 0x3e38aa3b, v212
	v_fmamk_f32 v28, v3, 0x3e38aa3b, v213
	v_mul_f32_e64 v1, -v145, v8
	v_max3_f32 v0, v0, v25, v28
	v_cndmask_b32_e32 v1, v183, v1, vcc
	v_add_f32_e32 v0, v1, v0
	v_mov_b32_e32 v2, v0
	s_nop 1
	v_permlane16_swap_b32_e32 v0, v2
	s_waitcnt lgkmcnt(0)
	v_max_f32_e32 v0, v0, v2
	v_mov_b32_e32 v2, v0
	s_nop 1
	v_permlane32_swap_b32_e32 v0, v2
	s_waitcnt lgkmcnt(0)
	v_max3_f32 v167, v32, v0, v2
	v_sub_f32_e32 v29, v167, v1
	v_sub_f32_e32 v0, v11, v29
	v_exp_f32_e32 v0, v0
	v_sub_f32_e32 v1, v12, v29
	v_exp_f32_e32 v1, v1
	v_add_f32_e32 v2, 0, v0
	v_add_f32_e32 v3, v1, v2
	v_sub_f32_e32 v2, v13, v29
	v_exp_f32_e32 v2, v2
	s_nop 0
	v_add_f32_e32 v4, v2, v3
	v_sub_f32_e32 v3, v14, v29
	v_exp_f32_e32 v3, v3
	s_nop 0
	v_add_f32_e32 v5, v3, v4
	v_sub_f32_e32 v4, v18, v29
	v_exp_f32_e32 v4, v4
	s_nop 0
	v_add_f32_e32 v6, v4, v5
	v_sub_f32_e32 v5, v19, v29
	v_exp_f32_e32 v5, v5
	s_nop 0
	v_add_f32_e32 v7, v5, v6
	v_sub_f32_e32 v6, v15, v29
	v_exp_f32_e32 v6, v6
	s_nop 0
	v_add_f32_e32 v8, v6, v7
	v_sub_f32_e32 v7, v20, v29
	v_exp_f32_e32 v7, v7
	s_nop 0
	v_add_f32_e32 v9, v7, v8
	v_sub_f32_e32 v8, v22, v29
	v_exp_f32_e32 v8, v8
	s_nop 0
	v_add_f32_e32 v10, v8, v9
	v_sub_f32_e32 v9, v23, v29
	v_exp_f32_e32 v9, v9
	s_nop 0
	v_add_f32_e32 v11, v9, v10
	v_sub_f32_e32 v10, v21, v29
	v_exp_f32_e32 v10, v10
	s_nop 0
	v_add_f32_e32 v12, v10, v11
	v_sub_f32_e32 v11, v24, v29
	v_exp_f32_e32 v11, v11
	s_nop 0
	v_add_f32_e32 v13, v11, v12
	v_sub_f32_e32 v12, v26, v29
	v_exp_f32_e32 v12, v12
	s_nop 0
	v_add_f32_e32 v14, v12, v13
	v_sub_f32_e32 v13, v27, v29
	v_exp_f32_e32 v13, v13
	s_nop 0
	v_add_f32_e32 v15, v13, v14
	v_sub_f32_e32 v14, v25, v29
	v_exp_f32_e32 v14, v14
	s_nop 0
	v_add_f32_e32 v18, v14, v15
	v_sub_f32_e32 v15, v28, v29
	v_exp_f32_e32 v15, v15
	s_nop 0
	v_add_f32_e32 v151, v15, v18
	s_cbranch_execnz .LBB0_165
	s_branch .LBB0_164

.LBB0_164:
	v_add_u32_e32 v4, v122, v199
	ds_read_b128 v[0:3], v4
	ds_read_b128 v[6:9], v4 offset:64
	v_cvt_f32_u32_e32 v139, v17
	v_and_b32_e32 v5, s25, v161
	v_cmp_eq_u32_e32 vcc, 0, v5
	v_add_u32_e32 v5, -1, v17
	v_cmp_lt_i32_e64 s[6:7], -1, v17
	s_waitcnt lgkmcnt(1)
	v_mfma_f32_16x16x32_bf16 v[0:3], v[0:3], v[34:37], 0
	ds_read_b128 v[10:13], v4 offset:2368
	ds_read_b128 v[18:21], v4 offset:4672
	s_waitcnt lgkmcnt(2)
	v_mfma_f32_16x16x32_bf16 v[0:3], v[6:9], v[38:41], v[0:3]
	s_nop 7
	v_mov_b32_e32 v144, v0
	v_pk_mul_f32 v[6:7], v[144:145], v[138:139]
	v_cvt_f32_u32_e32 v139, v5
	v_mov_b32_e32 v144, v1
	v_sub_f32_e32 v0, v6, v7
	v_cndmask_b32_e32 v0, v0, v183, vcc
	v_pk_mul_f32 v[6:7], v[144:145], v[138:139]
	v_cndmask_b32_e64 v0, v183, v0, s[6:7]
	v_sub_f32_e32 v1, v6, v7
	v_add_u32_e32 v6, -2, v17
	v_cvt_f32_u32_e32 v139, v6
	v_cmp_lt_i32_e64 s[6:7], -1, v5
	v_cndmask_b32_e32 v1, v1, v183, vcc
	v_mov_b32_e32 v144, v2
	v_cndmask_b32_e64 v1, v183, v1, s[6:7]
	v_cmp_lt_i32_e64 s[6:7], -1, v6
	v_pk_mul_f32 v[6:7], v[144:145], v[138:139]
	v_mov_b32_e32 v144, v3
	v_sub_f32_e32 v2, v6, v7
	v_add_u32_e32 v6, -3, v17
	v_cvt_f32_u32_e32 v139, v6
	v_cndmask_b32_e32 v2, v2, v183, vcc
	v_cndmask_b32_e64 v2, v183, v2, s[6:7]
	v_cmp_lt_i32_e64 s[6:7], -1, v6
	v_pk_mul_f32 v[6:7], v[144:145], v[138:139]
	v_max3_f32 v5, v0, s85, v1
	v_sub_f32_e32 v3, v6, v7
	ds_read_b128 v[6:9], v4 offset:2304
	s_waitcnt lgkmcnt(0)
	v_mfma_f32_16x16x32_bf16 v[6:9], v[6:9], v[34:37], 0
	v_cndmask_b32_e32 v3, v3, v183, vcc
	v_cndmask_b32_e64 v3, v183, v3, s[6:7]
	v_max3_f32 v14, v5, v2, v3
	v_mfma_f32_16x16x32_bf16 v[6:9], v[10:13], v[38:41], v[6:9]
	v_add_u32_e32 v5, -16, v17
	v_cvt_f32_u32_e32 v139, v5
	v_cmp_lt_i32_e64 s[6:7], -1, v5
	s_nop 4
	v_mov_b32_e32 v144, v6
	v_subrev_u32_e32 v6, 17, v17
	v_pk_mul_f32 v[10:11], v[144:145], v[138:139]
	v_cvt_f32_u32_e32 v139, v6
	v_sub_f32_e32 v5, v10, v11
	v_cndmask_b32_e32 v5, v5, v183, vcc
	v_mov_b32_e32 v144, v7
	v_cndmask_b32_e64 v5, v183, v5, s[6:7]
	v_cmp_lt_i32_e64 s[6:7], -1, v6
	v_pk_mul_f32 v[6:7], v[144:145], v[138:139]
	v_mov_b32_e32 v144, v8
	v_sub_f32_e32 v6, v6, v7
	v_subrev_u32_e32 v7, 18, v17
	v_cvt_f32_u32_e32 v139, v7
	v_cndmask_b32_e32 v6, v6, v183, vcc
	v_cndmask_b32_e64 v6, v183, v6, s[6:7]
	v_cmp_lt_i32_e64 s[6:7], -1, v7
	v_pk_mul_f32 v[10:11], v[144:145], v[138:139]
	v_mov_b32_e32 v144, v9
	v_sub_f32_e32 v7, v10, v11
	v_cndmask_b32_e32 v7, v7, v183, vcc
	v_cndmask_b32_e64 v8, v183, v7, s[6:7]
	v_subrev_u32_e32 v7, 19, v17
	v_cvt_f32_u32_e32 v139, v7
	v_cmp_lt_i32_e64 s[6:7], -1, v7
	v_max3_f32 v12, v14, v5, v6
	v_subrev_u32_e32 v14, 32, v17
	v_pk_mul_f32 v[10:11], v[144:145], v[138:139]
	v_cvt_f32_u32_e32 v139, v14
	v_sub_f32_e32 v7, v10, v11
	v_cndmask_b32_e32 v7, v7, v183, vcc
	v_cndmask_b32_e64 v7, v183, v7, s[6:7]
	v_max3_f32 v9, v12, v8, v7
	ds_read_b128 v[10:13], v4 offset:4608
	s_waitcnt lgkmcnt(0)
	v_mfma_f32_16x16x32_bf16 v[10:13], v[10:13], v[34:37], 0
	v_cmp_lt_i32_e64 s[6:7], -1, v14
	v_mfma_f32_16x16x32_bf16 v[10:13], v[18:21], v[38:41], v[10:13]
	ds_read_b128 v[18:21], v4 offset:6976
	s_nop 6
	v_mov_b32_e32 v144, v10
	v_pk_mul_f32 v[14:15], v[144:145], v[138:139]
	v_mov_b32_e32 v144, v11
	v_sub_f32_e32 v10, v14, v15
	v_cndmask_b32_e32 v10, v10, v183, vcc
	v_cndmask_b32_e64 v22, v183, v10, s[6:7]
	v_subrev_u32_e32 v10, 33, v17
	v_cvt_f32_u32_e32 v139, v10
	v_cmp_lt_i32_e64 s[6:7], -1, v10
	v_pk_mul_f32 v[10:11], v[144:145], v[138:139]
	s_nop 0
	v_sub_f32_e32 v10, v10, v11
	v_cndmask_b32_e32 v10, v10, v183, vcc
	v_cndmask_b32_e64 v23, v183, v10, s[6:7]
	v_subrev_u32_e32 v10, 34, v17
	v_cvt_f32_u32_e32 v139, v10
	v_mov_b32_e32 v144, v12
	v_cmp_lt_i32_e64 s[6:7], -1, v10
	v_max3_f32 v9, v9, v22, v23
	v_pk_mul_f32 v[10:11], v[144:145], v[138:139]
	v_mov_b32_e32 v144, v13
	v_sub_f32_e32 v10, v10, v11
	v_cndmask_b32_e32 v10, v10, v183, vcc
	v_cndmask_b32_e64 v24, v183, v10, s[6:7]
	v_subrev_u32_e32 v10, 35, v17
	v_cvt_f32_u32_e32 v139, v10
	v_cmp_lt_i32_e64 s[6:7], -1, v10
	v_pk_mul_f32 v[10:11], v[144:145], v[138:139]
	s_nop 0
	v_sub_f32_e32 v10, v10, v11
	v_cndmask_b32_e32 v10, v10, v183, vcc
	v_cndmask_b32_e64 v25, v183, v10, s[6:7]
	ds_read_b128 v[10:13], v4 offset:6912
	s_waitcnt lgkmcnt(0)
	v_mfma_f32_16x16x32_bf16 v[10:13], v[10:13], v[34:37], 0
	v_subrev_u32_e32 v4, 48, v17
	v_cvt_f32_u32_e32 v139, v4
	v_cmp_lt_i32_e64 s[6:7], -1, v4
	v_mfma_f32_16x16x32_bf16 v[10:13], v[18:21], v[38:41], v[10:13]
	v_max3_f32 v9, v9, v24, v25
	s_nop 6
	v_mov_b32_e32 v144, v10
	v_pk_mul_f32 v[14:15], v[144:145], v[138:139]
	v_mov_b32_e32 v144, v11
	v_sub_f32_e32 v4, v14, v15
	v_cndmask_b32_e32 v4, v4, v183, vcc
	v_cndmask_b32_e64 v14, v183, v4, s[6:7]
	v_subrev_u32_e32 v4, 49, v17
	v_cvt_f32_u32_e32 v139, v4
	v_cmp_lt_i32_e64 s[6:7], -1, v4
	v_pk_mul_f32 v[10:11], v[144:145], v[138:139]
	s_nop 0
	v_sub_f32_e32 v4, v10, v11
	v_cndmask_b32_e32 v4, v4, v183, vcc
	v_cndmask_b32_e64 v15, v183, v4, s[6:7]
	v_max3_f32 v4, v9, v14, v15
	v_subrev_u32_e32 v9, 50, v17
	v_cvt_f32_u32_e32 v139, v9
	v_mov_b32_e32 v144, v12
	v_cmp_lt_i32_e64 s[6:7], -1, v9
	v_pk_mul_f32 v[10:11], v[144:145], v[138:139]
	s_nop 0
	v_sub_f32_e32 v9, v10, v11
	v_cndmask_b32_e32 v9, v9, v183, vcc
	v_cndmask_b32_e64 v18, v183, v9, s[6:7]
	v_subrev_u32_e32 v9, 51, v17
	v_cvt_f32_u32_e32 v139, v9
	v_mov_b32_e32 v144, v13
	v_cmp_lt_i32_e64 s[6:7], -1, v9
	v_pk_mul_f32 v[10:11], v[144:145], v[138:139]
	s_nop 0
	v_sub_f32_e32 v9, v10, v11
	v_cndmask_b32_e32 v9, v9, v183, vcc
	v_cndmask_b32_e64 v17, v183, v9, s[6:7]
	v_max3_f32 v4, v4, v18, v17
	v_mov_b32_e32 v9, v4
	s_nop 1
	v_permlane16_swap_b32_e32 v4, v9
	v_cmp_lt_f32_e32 vcc, s39, v0
	s_waitcnt lgkmcnt(0)
	v_max_f32_e32 v4, v4, v9
	v_mov_b32_e32 v9, v4
	s_nop 1
	v_permlane32_swap_b32_e32 v4, v9
	s_waitcnt lgkmcnt(0)
	v_max3_f32 v167, v32, v4, v9
	v_sub_f32_e32 v0, v0, v167
	v_exp_f32_e32 v0, v0
	s_nop 0
	v_cndmask_b32_e32 v0, 0, v0, vcc
	v_cmp_lt_f32_e32 vcc, s39, v1
	v_sub_f32_e32 v1, v1, v167
	v_exp_f32_e32 v1, v1
	v_add_f32_e32 v4, 0, v0
	v_cndmask_b32_e32 v1, 0, v1, vcc
	v_cmp_lt_f32_e32 vcc, s39, v2
	v_sub_f32_e32 v2, v2, v167
	v_exp_f32_e32 v2, v2
	v_add_f32_e32 v4, v1, v4
	v_cndmask_b32_e32 v2, 0, v2, vcc
	v_cmp_lt_f32_e32 vcc, s39, v3
	v_sub_f32_e32 v3, v3, v167
	v_exp_f32_e32 v3, v3
	v_add_f32_e32 v4, v2, v4
	v_cndmask_b32_e32 v3, 0, v3, vcc
	v_add_f32_e32 v9, v3, v4
	v_sub_f32_e32 v4, v5, v167
	v_exp_f32_e32 v4, v4
	v_cmp_lt_f32_e32 vcc, s39, v5
	v_sub_f32_e32 v5, v6, v167
	v_exp_f32_e32 v5, v5
	v_cndmask_b32_e32 v4, 0, v4, vcc
	v_cmp_lt_f32_e32 vcc, s39, v6
	v_sub_f32_e32 v6, v8, v167
	v_exp_f32_e32 v6, v6
	v_cndmask_b32_e32 v5, 0, v5, vcc
	v_cmp_lt_f32_e32 vcc, s39, v8
	v_add_f32_e32 v9, v4, v9
	v_add_f32_e32 v9, v5, v9
	v_cndmask_b32_e32 v6, 0, v6, vcc
	v_cmp_lt_f32_e32 vcc, s39, v7
	v_sub_f32_e32 v7, v7, v167
	v_exp_f32_e32 v7, v7
	v_add_f32_e32 v8, v6, v9
	v_cndmask_b32_e32 v7, 0, v7, vcc
	v_add_f32_e32 v9, v7, v8
	v_sub_f32_e32 v8, v22, v167
	v_exp_f32_e32 v8, v8
	v_cmp_lt_f32_e32 vcc, s39, v22
	s_nop 1
	v_cndmask_b32_e32 v8, 0, v8, vcc
	v_add_f32_e32 v10, v8, v9
	v_sub_f32_e32 v9, v23, v167
	v_exp_f32_e32 v9, v9
	v_cmp_lt_f32_e32 vcc, s39, v23
	s_nop 1
	v_cndmask_b32_e32 v9, 0, v9, vcc
	v_add_f32_e32 v11, v9, v10
	v_sub_f32_e32 v10, v24, v167
	v_exp_f32_e32 v10, v10
	v_cmp_lt_f32_e32 vcc, s39, v24
	s_nop 1
	v_cndmask_b32_e32 v10, 0, v10, vcc
	v_add_f32_e32 v12, v10, v11
	v_sub_f32_e32 v11, v25, v167
	v_exp_f32_e32 v11, v11
	v_cmp_lt_f32_e32 vcc, s39, v25
	s_nop 1
	v_cndmask_b32_e32 v11, 0, v11, vcc
	v_add_f32_e32 v13, v11, v12
	v_sub_f32_e32 v12, v14, v167
	v_exp_f32_e32 v12, v12
	v_cmp_lt_f32_e32 vcc, s39, v14
	s_nop 1
	v_cndmask_b32_e32 v12, 0, v12, vcc
	v_add_f32_e32 v14, v12, v13
	v_sub_f32_e32 v13, v15, v167
	v_exp_f32_e32 v13, v13
	v_cmp_lt_f32_e32 vcc, s39, v15
	s_nop 1
	v_cndmask_b32_e32 v13, 0, v13, vcc
	v_add_f32_e32 v15, v13, v14
	v_sub_f32_e32 v14, v18, v167
	v_exp_f32_e32 v14, v14
	v_cmp_lt_f32_e32 vcc, s39, v18
	s_nop 1
	v_cndmask_b32_e32 v14, 0, v14, vcc
	v_add_f32_e32 v18, v14, v15
	v_sub_f32_e32 v15, v17, v167
	v_exp_f32_e32 v15, v15
	v_cmp_lt_f32_e32 vcc, s39, v17
	s_nop 1
	v_cndmask_b32_e32 v15, 0, v15, vcc
	v_add_f32_e32 v151, v15, v18
.LBB0_165:
	v_add_u32_e32 v123, v16, v142
	s_andn2_b64 vcc, exec, s[42:43]
	s_mov_b64 s[6:7], -1
	s_cbranch_vccnz .LBB0_167
	v_add_u32_e32 v26, v122, v199
	ds_read_b128 v[16:19], v26
	ds_read_b128 v[20:23], v26 offset:64
	v_cvt_f32_i32_e32 v24, v123
	v_and_b32_e32 v25, s25, v160
	v_cmp_ne_u32_e32 vcc, 0, v25
	s_waitcnt lgkmcnt(1)
	v_mfma_f32_16x16x32_bf16 v[16:19], v[16:19], v[42:45], 0
	s_waitcnt lgkmcnt(0)
	v_mfma_f32_16x16x32_bf16 v[16:19], v[20:23], v[46:49], v[16:19]
	ds_read_b128 v[20:23], v26 offset:2368
	s_nop 6
	v_fmamk_f32 v27, v16, 0x3e38aa3b, v137
	v_fmamk_f32 v28, v17, 0x3e38aa3b, v145
	v_max3_f32 v16, v27, s85, v28
	v_fmamk_f32 v29, v18, 0x3e38aa3b, v200
	v_fmamk_f32 v30, v19, 0x3e38aa3b, v201
	v_max3_f32 v31, v16, v29, v30
	ds_read_b128 v[16:19], v26 offset:2304
	s_waitcnt lgkmcnt(0)
	v_mfma_f32_16x16x32_bf16 v[16:19], v[16:19], v[42:45], 0
	v_mfma_f32_16x16x32_bf16 v[16:19], v[20:23], v[46:49], v[16:19]
	ds_read_b128 v[20:23], v26 offset:4672
	s_nop 6
	v_fmamk_f32 v124, v16, 0x3e38aa3b, v202
	v_fmamk_f32 v125, v17, 0x3e38aa3b, v203
	v_max3_f32 v16, v31, v124, v125
	v_fmamk_f32 v31, v18, 0x3e38aa3b, v204
	v_fmamk_f32 v126, v19, 0x3e38aa3b, v205
	v_max3_f32 v127, v16, v31, v126
	ds_read_b128 v[16:19], v26 offset:4608
	s_waitcnt lgkmcnt(0)
	v_mfma_f32_16x16x32_bf16 v[16:19], v[16:19], v[42:45], 0
	v_mfma_f32_16x16x32_bf16 v[16:19], v[20:23], v[46:49], v[16:19]
	ds_read_b128 v[20:23], v26 offset:6976
	s_nop 6
	v_fmamk_f32 v128, v16, 0x3e38aa3b, v206
	v_fmamk_f32 v129, v17, 0x3e38aa3b, v207
	v_max3_f32 v16, v127, v128, v129
	v_fmamk_f32 v127, v18, 0x3e38aa3b, v208
	v_fmamk_f32 v144, v19, 0x3e38aa3b, v209
	v_max3_f32 v139, v16, v127, v144
	ds_read_b128 v[16:19], v26 offset:6912
	s_waitcnt lgkmcnt(0)
	v_mfma_f32_16x16x32_bf16 v[16:19], v[16:19], v[42:45], 0
	v_mfma_f32_16x16x32_bf16 v[16:19], v[20:23], v[46:49], v[16:19]
	s_nop 7
	v_fmamk_f32 v150, v16, 0x3e38aa3b, v210
	v_fmamk_f32 v168, v17, 0x3e38aa3b, v211
	v_max3_f32 v16, v139, v150, v168
	v_fmamk_f32 v169, v18, 0x3e38aa3b, v212
	v_fmamk_f32 v214, v19, 0x3e38aa3b, v213
	v_mul_f32_e64 v17, -v145, v24
	v_max3_f32 v16, v16, v169, v214
	v_cndmask_b32_e32 v17, v183, v17, vcc
	v_add_f32_e32 v16, v17, v16
	v_mov_b32_e32 v18, v16
	s_nop 1
	v_permlane16_swap_b32_e32 v16, v18
	s_waitcnt lgkmcnt(0)
	v_max_f32_e32 v16, v16, v18
	v_mov_b32_e32 v18, v16
	s_nop 1
	v_permlane32_swap_b32_e32 v16, v18
	s_waitcnt lgkmcnt(0)
	v_max3_f32 v139, v166, v16, v18
	v_sub_f32_e32 v215, v139, v17
	v_sub_f32_e32 v16, v27, v215
	v_exp_f32_e32 v16, v16
	v_sub_f32_e32 v17, v28, v215
	v_exp_f32_e32 v17, v17
	v_add_f32_e32 v18, 0, v16
	v_add_f32_e32 v19, v17, v18
	v_sub_f32_e32 v18, v29, v215
	v_exp_f32_e32 v18, v18
	s_nop 0
	v_add_f32_e32 v20, v18, v19
	v_sub_f32_e32 v19, v30, v215
	v_exp_f32_e32 v19, v19
	s_nop 0
	v_add_f32_e32 v21, v19, v20
	v_sub_f32_e32 v20, v124, v215
	v_exp_f32_e32 v20, v20
	s_nop 0
	v_add_f32_e32 v22, v20, v21
	v_sub_f32_e32 v21, v125, v215
	v_exp_f32_e32 v21, v21
	s_nop 0
	v_add_f32_e32 v23, v21, v22
	v_sub_f32_e32 v22, v31, v215
	v_exp_f32_e32 v22, v22
	s_nop 0
	v_add_f32_e32 v24, v22, v23
	v_sub_f32_e32 v23, v126, v215
	v_exp_f32_e32 v23, v23
	s_nop 0
	v_add_f32_e32 v25, v23, v24
	v_sub_f32_e32 v24, v128, v215
	v_exp_f32_e32 v24, v24
	s_nop 0
	v_add_f32_e32 v26, v24, v25
	v_sub_f32_e32 v25, v129, v215
	v_exp_f32_e32 v25, v25
	s_nop 0
	v_add_f32_e32 v27, v25, v26
	v_sub_f32_e32 v26, v127, v215
	v_exp_f32_e32 v26, v26
	s_nop 0
	v_add_f32_e32 v28, v26, v27
	v_sub_f32_e32 v27, v144, v215
	v_exp_f32_e32 v27, v27
	s_nop 0
	v_add_f32_e32 v29, v27, v28
	v_sub_f32_e32 v28, v150, v215
	v_exp_f32_e32 v28, v28
	s_nop 0
	v_add_f32_e32 v30, v28, v29
	v_sub_f32_e32 v29, v168, v215
	v_exp_f32_e32 v29, v29
	s_nop 0
	v_add_f32_e32 v31, v29, v30
	v_sub_f32_e32 v30, v169, v215
	v_exp_f32_e32 v30, v30
	s_nop 0
	v_add_f32_e32 v124, v30, v31
	v_sub_f32_e32 v31, v214, v215
	v_exp_f32_e32 v31, v31
	s_nop 0
	v_add_f32_e32 v150, v31, v124
	s_cbranch_execz .LBB0_168
	s_branch .LBB0_169

.LBB0_168:
	v_add_u32_e32 v20, v122, v199
	ds_read_b128 v[16:19], v20
	ds_read_b128 v[22:25], v20 offset:64
	v_cvt_f32_u32_e32 v139, v123
	v_and_b32_e32 v21, s25, v160
	v_cmp_eq_u32_e32 vcc, 0, v21
	v_add_u32_e32 v21, -1, v123
	v_cmp_lt_i32_e64 s[6:7], -1, v123
	s_waitcnt lgkmcnt(1)
	v_mfma_f32_16x16x32_bf16 v[16:19], v[16:19], v[42:45], 0
	ds_read_b128 v[26:29], v20 offset:2368
	ds_read_b128 v[124:127], v20 offset:4672
	s_waitcnt lgkmcnt(2)
	v_mfma_f32_16x16x32_bf16 v[16:19], v[22:25], v[46:49], v[16:19]
	s_nop 7
	v_mov_b32_e32 v144, v16
	v_pk_mul_f32 v[22:23], v[144:145], v[138:139]
	v_cvt_f32_u32_e32 v139, v21
	v_mov_b32_e32 v144, v17
	v_sub_f32_e32 v16, v22, v23
	v_cndmask_b32_e32 v16, v16, v183, vcc
	v_pk_mul_f32 v[22:23], v[144:145], v[138:139]
	v_cndmask_b32_e64 v16, v183, v16, s[6:7]
	v_sub_f32_e32 v17, v22, v23
	v_add_u32_e32 v22, -2, v123
	v_cvt_f32_u32_e32 v139, v22
	v_cmp_lt_i32_e64 s[6:7], -1, v21
	v_cndmask_b32_e32 v17, v17, v183, vcc
	v_mov_b32_e32 v144, v18
	v_cndmask_b32_e64 v17, v183, v17, s[6:7]
	v_cmp_lt_i32_e64 s[6:7], -1, v22
	v_pk_mul_f32 v[22:23], v[144:145], v[138:139]
	v_mov_b32_e32 v144, v19
	v_sub_f32_e32 v18, v22, v23
	v_add_u32_e32 v22, -3, v123
	v_cvt_f32_u32_e32 v139, v22
	v_cndmask_b32_e32 v18, v18, v183, vcc
	v_cndmask_b32_e64 v18, v183, v18, s[6:7]
	v_cmp_lt_i32_e64 s[6:7], -1, v22
	v_pk_mul_f32 v[22:23], v[144:145], v[138:139]
	v_max3_f32 v21, v16, s85, v17
	v_sub_f32_e32 v19, v22, v23
	ds_read_b128 v[22:25], v20 offset:2304
	s_waitcnt lgkmcnt(0)
	v_mfma_f32_16x16x32_bf16 v[22:25], v[22:25], v[42:45], 0
	v_cndmask_b32_e32 v19, v19, v183, vcc
	v_cndmask_b32_e64 v19, v183, v19, s[6:7]
	v_max3_f32 v30, v21, v18, v19
	v_mfma_f32_16x16x32_bf16 v[22:25], v[26:29], v[46:49], v[22:25]
	v_add_u32_e32 v21, -16, v123
	v_cvt_f32_u32_e32 v139, v21
	v_cmp_lt_i32_e64 s[6:7], -1, v21
	s_nop 4
	v_mov_b32_e32 v144, v22
	v_subrev_u32_e32 v22, 17, v123
	v_pk_mul_f32 v[26:27], v[144:145], v[138:139]
	v_cvt_f32_u32_e32 v139, v22
	v_sub_f32_e32 v21, v26, v27
	v_cndmask_b32_e32 v21, v21, v183, vcc
	v_mov_b32_e32 v144, v23
	v_cndmask_b32_e64 v21, v183, v21, s[6:7]
	v_cmp_lt_i32_e64 s[6:7], -1, v22
	v_pk_mul_f32 v[22:23], v[144:145], v[138:139]
	v_mov_b32_e32 v144, v24
	v_sub_f32_e32 v22, v22, v23
	v_subrev_u32_e32 v23, 18, v123
	v_cvt_f32_u32_e32 v139, v23
	v_cndmask_b32_e32 v22, v22, v183, vcc
	v_cndmask_b32_e64 v22, v183, v22, s[6:7]
	v_cmp_lt_i32_e64 s[6:7], -1, v23
	v_pk_mul_f32 v[26:27], v[144:145], v[138:139]
	v_mov_b32_e32 v144, v25
	v_sub_f32_e32 v23, v26, v27
	v_cndmask_b32_e32 v23, v23, v183, vcc
	v_cndmask_b32_e64 v24, v183, v23, s[6:7]
	v_subrev_u32_e32 v23, 19, v123
	v_cvt_f32_u32_e32 v139, v23
	v_cmp_lt_i32_e64 s[6:7], -1, v23
	v_max3_f32 v28, v30, v21, v22
	v_subrev_u32_e32 v30, 32, v123
	v_pk_mul_f32 v[26:27], v[144:145], v[138:139]
	v_cvt_f32_u32_e32 v139, v30
	v_sub_f32_e32 v23, v26, v27
	v_cndmask_b32_e32 v23, v23, v183, vcc
	v_cndmask_b32_e64 v23, v183, v23, s[6:7]
	v_max3_f32 v25, v28, v24, v23
	ds_read_b128 v[26:29], v20 offset:4608
	s_waitcnt lgkmcnt(0)
	v_mfma_f32_16x16x32_bf16 v[26:29], v[26:29], v[42:45], 0
	v_cmp_lt_i32_e64 s[6:7], -1, v30
	v_mfma_f32_16x16x32_bf16 v[26:29], v[124:127], v[46:49], v[26:29]
	ds_read_b128 v[124:127], v20 offset:6976
	s_nop 6
	v_mov_b32_e32 v144, v26
	v_pk_mul_f32 v[30:31], v[144:145], v[138:139]
	v_mov_b32_e32 v144, v27
	v_sub_f32_e32 v26, v30, v31
	v_cndmask_b32_e32 v26, v26, v183, vcc
	v_cndmask_b32_e64 v122, v183, v26, s[6:7]
	v_subrev_u32_e32 v26, 33, v123
	v_cvt_f32_u32_e32 v139, v26
	v_cmp_lt_i32_e64 s[6:7], -1, v26
	v_pk_mul_f32 v[26:27], v[144:145], v[138:139]
	s_nop 0
	v_sub_f32_e32 v26, v26, v27
	v_cndmask_b32_e32 v26, v26, v183, vcc
	v_cndmask_b32_e64 v128, v183, v26, s[6:7]
	v_subrev_u32_e32 v26, 34, v123
	v_cvt_f32_u32_e32 v139, v26
	v_mov_b32_e32 v144, v28
	v_cmp_lt_i32_e64 s[6:7], -1, v26
	v_max3_f32 v25, v25, v122, v128
	v_pk_mul_f32 v[26:27], v[144:145], v[138:139]
	v_mov_b32_e32 v144, v29
	v_sub_f32_e32 v26, v26, v27
	v_cndmask_b32_e32 v26, v26, v183, vcc
	v_cndmask_b32_e64 v129, v183, v26, s[6:7]
	v_subrev_u32_e32 v26, 35, v123
	v_cvt_f32_u32_e32 v139, v26
	v_cmp_lt_i32_e64 s[6:7], -1, v26
	v_pk_mul_f32 v[26:27], v[144:145], v[138:139]
	s_nop 0
	v_sub_f32_e32 v26, v26, v27
	v_cndmask_b32_e32 v26, v26, v183, vcc
	v_cndmask_b32_e64 v150, v183, v26, s[6:7]
	ds_read_b128 v[26:29], v20 offset:6912
	s_waitcnt lgkmcnt(0)
	v_mfma_f32_16x16x32_bf16 v[26:29], v[26:29], v[42:45], 0
	v_subrev_u32_e32 v20, 48, v123
	v_cvt_f32_u32_e32 v139, v20
	v_cmp_lt_i32_e64 s[6:7], -1, v20
	v_mfma_f32_16x16x32_bf16 v[26:29], v[124:127], v[46:49], v[26:29]
	v_max3_f32 v25, v25, v129, v150
	s_nop 6
	v_mov_b32_e32 v144, v26
	v_pk_mul_f32 v[30:31], v[144:145], v[138:139]
	v_mov_b32_e32 v144, v27
	v_sub_f32_e32 v20, v30, v31
	v_cndmask_b32_e32 v20, v20, v183, vcc
	v_cndmask_b32_e64 v30, v183, v20, s[6:7]
	v_subrev_u32_e32 v20, 49, v123
	v_cvt_f32_u32_e32 v139, v20
	v_cmp_lt_i32_e64 s[6:7], -1, v20
	v_pk_mul_f32 v[26:27], v[144:145], v[138:139]
	s_nop 0
	v_sub_f32_e32 v20, v26, v27
	v_cndmask_b32_e32 v20, v20, v183, vcc
	v_cndmask_b32_e64 v31, v183, v20, s[6:7]
	v_max3_f32 v20, v25, v30, v31
	v_subrev_u32_e32 v25, 50, v123
	v_cvt_f32_u32_e32 v139, v25
	v_mov_b32_e32 v144, v28
	v_cmp_lt_i32_e64 s[6:7], -1, v25
	v_pk_mul_f32 v[26:27], v[144:145], v[138:139]
	s_nop 0
	v_sub_f32_e32 v25, v26, v27
	v_cndmask_b32_e32 v25, v25, v183, vcc
	v_cndmask_b32_e64 v124, v183, v25, s[6:7]
	v_subrev_u32_e32 v25, 51, v123
	v_cvt_f32_u32_e32 v139, v25
	v_mov_b32_e32 v144, v29
	v_cmp_lt_i32_e64 s[6:7], -1, v25
	v_pk_mul_f32 v[26:27], v[144:145], v[138:139]
	s_nop 0
	v_sub_f32_e32 v25, v26, v27
	v_cndmask_b32_e32 v25, v25, v183, vcc
	v_cndmask_b32_e64 v123, v183, v25, s[6:7]
	v_max3_f32 v20, v20, v124, v123
	v_mov_b32_e32 v25, v20
	s_nop 1
	v_permlane16_swap_b32_e32 v20, v25
	v_cmp_lt_f32_e32 vcc, s39, v16
	s_waitcnt lgkmcnt(0)
	v_max_f32_e32 v20, v20, v25
	v_mov_b32_e32 v25, v20
	s_nop 1
	v_permlane32_swap_b32_e32 v20, v25
	s_waitcnt lgkmcnt(0)
	v_max3_f32 v139, v166, v20, v25
	v_sub_f32_e32 v16, v16, v139
	v_exp_f32_e32 v16, v16
	s_nop 0
	v_cndmask_b32_e32 v16, 0, v16, vcc
	v_cmp_lt_f32_e32 vcc, s39, v17
	v_sub_f32_e32 v17, v17, v139
	v_exp_f32_e32 v17, v17
	v_add_f32_e32 v20, 0, v16
	v_cndmask_b32_e32 v17, 0, v17, vcc
	v_cmp_lt_f32_e32 vcc, s39, v18
	v_sub_f32_e32 v18, v18, v139
	v_exp_f32_e32 v18, v18
	v_add_f32_e32 v20, v17, v20
	v_cndmask_b32_e32 v18, 0, v18, vcc
	v_cmp_lt_f32_e32 vcc, s39, v19
	v_sub_f32_e32 v19, v19, v139
	v_exp_f32_e32 v19, v19
	v_add_f32_e32 v20, v18, v20
	v_cndmask_b32_e32 v19, 0, v19, vcc
	v_add_f32_e32 v25, v19, v20
	v_sub_f32_e32 v20, v21, v139
	v_exp_f32_e32 v20, v20
	v_cmp_lt_f32_e32 vcc, s39, v21
	v_sub_f32_e32 v21, v22, v139
	v_exp_f32_e32 v21, v21
	v_cndmask_b32_e32 v20, 0, v20, vcc
	v_cmp_lt_f32_e32 vcc, s39, v22
	v_sub_f32_e32 v22, v24, v139
	v_exp_f32_e32 v22, v22
	v_cndmask_b32_e32 v21, 0, v21, vcc
	v_cmp_lt_f32_e32 vcc, s39, v24
	v_add_f32_e32 v25, v20, v25
	v_add_f32_e32 v25, v21, v25
	v_cndmask_b32_e32 v22, 0, v22, vcc
	v_cmp_lt_f32_e32 vcc, s39, v23
	v_sub_f32_e32 v23, v23, v139
	v_exp_f32_e32 v23, v23
	v_add_f32_e32 v24, v22, v25
	v_cndmask_b32_e32 v23, 0, v23, vcc
	v_add_f32_e32 v25, v23, v24
	v_sub_f32_e32 v24, v122, v139
	v_exp_f32_e32 v24, v24
	v_cmp_lt_f32_e32 vcc, s39, v122
	s_nop 1
	v_cndmask_b32_e32 v24, 0, v24, vcc
	v_add_f32_e32 v26, v24, v25
	v_sub_f32_e32 v25, v128, v139
	v_exp_f32_e32 v25, v25
	v_cmp_lt_f32_e32 vcc, s39, v128
	s_nop 1
	v_cndmask_b32_e32 v25, 0, v25, vcc
	v_add_f32_e32 v27, v25, v26
	v_sub_f32_e32 v26, v129, v139
	v_exp_f32_e32 v26, v26
	v_cmp_lt_f32_e32 vcc, s39, v129
	s_nop 1
	v_cndmask_b32_e32 v26, 0, v26, vcc
	v_add_f32_e32 v28, v26, v27
	v_sub_f32_e32 v27, v150, v139
	v_exp_f32_e32 v27, v27
	v_cmp_lt_f32_e32 vcc, s39, v150
	s_nop 1
	v_cndmask_b32_e32 v27, 0, v27, vcc
	v_add_f32_e32 v29, v27, v28
	v_sub_f32_e32 v28, v30, v139
	v_exp_f32_e32 v28, v28
	v_cmp_lt_f32_e32 vcc, s39, v30
	s_nop 1
	v_cndmask_b32_e32 v28, 0, v28, vcc
	v_add_f32_e32 v30, v28, v29
	v_sub_f32_e32 v29, v31, v139
	v_exp_f32_e32 v29, v29
	v_cmp_lt_f32_e32 vcc, s39, v31
	s_nop 1
	v_cndmask_b32_e32 v29, 0, v29, vcc
	v_add_f32_e32 v31, v29, v30
	v_sub_f32_e32 v30, v124, v139
	v_exp_f32_e32 v30, v30
	v_cmp_lt_f32_e32 vcc, s39, v124
	s_nop 1
	v_cndmask_b32_e32 v30, 0, v30, vcc
	v_add_f32_e32 v122, v30, v31
	v_sub_f32_e32 v31, v123, v139
	v_exp_f32_e32 v31, v31
	v_cmp_lt_f32_e32 vcc, s39, v123
	s_nop 1
	v_cndmask_b32_e32 v31, 0, v31, vcc
	v_add_f32_e32 v150, v31, v122

.LBB0_177:
	s_add_i32 s0, s20, s0
	s_cmp_lg_u32 s0, -1
	s_cselect_b64 s[0:1], -1, 0
	s_cmp_gt_i32 s23, s18
	s_cselect_b64 s[6:7], -1, 0
	s_mul_i32 s25, s19, 0x2400
	s_and_b64 s[6:7], s[0:1], s[6:7]
	v_add_u32_e32 v122, s25, v197
	v_add_u32_e32 v153, -16, v221
	s_mov_b64 s[40:41], -1
	s_and_b64 vcc, exec, s[6:7]
	s_cbranch_vccz .LBB0_179
	v_add_u32_e32 v128, v122, v199
	ds_read_b128 v[124:127], v128
	ds_read_b128 v[154:157], v128 offset:64
	v_cvt_f32_i32_e32 v123, v153
	s_waitcnt lgkmcnt(1)
	v_mfma_f32_16x16x32_bf16 v[124:127], v[124:127], v[34:37], 0
	s_waitcnt lgkmcnt(0)
	v_mfma_f32_16x16x32_bf16 v[124:127], v[154:157], v[38:41], v[124:127]
	ds_read_b128 v[154:157], v128 offset:2368
	s_nop 6
	v_fmamk_f32 v129, v124, 0x3e38aa3b, v137
	v_fmamk_f32 v139, v125, 0x3e38aa3b, v145
	v_max3_f32 v124, v129, s85, v139
	v_fmamk_f32 v144, v126, 0x3e38aa3b, v200
	v_fmamk_f32 v150, v127, 0x3e38aa3b, v201
	v_max3_f32 v151, v124, v144, v150
	ds_read_b128 v[124:127], v128 offset:2304
	s_waitcnt lgkmcnt(0)
	v_mfma_f32_16x16x32_bf16 v[124:127], v[124:127], v[34:37], 0
	v_mfma_f32_16x16x32_bf16 v[124:127], v[154:157], v[38:41], v[124:127]
	ds_read_b128 v[154:157], v128 offset:4672
	s_nop 6
	v_fmamk_f32 v152, v124, 0x3e38aa3b, v202
	v_fmamk_f32 v158, v125, 0x3e38aa3b, v203
	v_max3_f32 v124, v151, v152, v158
	v_fmamk_f32 v151, v126, 0x3e38aa3b, v204
	v_fmamk_f32 v159, v127, 0x3e38aa3b, v205
	v_max3_f32 v160, v124, v151, v159
	ds_read_b128 v[124:127], v128 offset:4608
	s_waitcnt lgkmcnt(0)
	v_mfma_f32_16x16x32_bf16 v[124:127], v[124:127], v[34:37], 0
	v_mfma_f32_16x16x32_bf16 v[124:127], v[154:157], v[38:41], v[124:127]
	ds_read_b128 v[154:157], v128 offset:6976
	s_nop 6
	v_fmamk_f32 v161, v124, 0x3e38aa3b, v206
	v_fmamk_f32 v162, v125, 0x3e38aa3b, v207
	v_max3_f32 v124, v160, v161, v162
	v_fmamk_f32 v160, v126, 0x3e38aa3b, v208
	v_fmamk_f32 v163, v127, 0x3e38aa3b, v209
	v_max3_f32 v164, v124, v160, v163
	ds_read_b128 v[124:127], v128 offset:6912
	s_waitcnt lgkmcnt(0)
	v_mfma_f32_16x16x32_bf16 v[124:127], v[124:127], v[34:37], 0
	v_mfma_f32_16x16x32_bf16 v[124:127], v[154:157], v[38:41], v[124:127]
	s_nop 7
	v_fmamk_f32 v124, v124, 0x3e38aa3b, v210
	v_fmamk_f32 v125, v125, 0x3e38aa3b, v211
	v_max3_f32 v128, v164, v124, v125
	v_fmamk_f32 v126, v126, 0x3e38aa3b, v212
	v_fmamk_f32 v127, v127, 0x3e38aa3b, v213
	v_max3_f32 v128, v128, v126, v127
	v_fma_f32 v128, -v145, v123, v128
	v_mov_b32_e32 v154, v128
	s_nop 1
	v_permlane16_swap_b32_e32 v128, v154
	s_waitcnt lgkmcnt(0)
	v_max_f32_e32 v128, v128, v154
	v_mov_b32_e32 v154, v128
	s_nop 1
	v_permlane32_swap_b32_e32 v128, v154
	s_waitcnt lgkmcnt(0)
	v_max3_f32 v225, v32, v128, v154
	v_fma_f32 v123, v145, v123, v225
	v_sub_f32_e32 v128, v129, v123
	v_exp_f32_e32 v240, v128
	v_sub_f32_e32 v129, v139, v123
	v_exp_f32_e32 v241, v129
	v_sub_f32_e32 v129, v144, v123
	v_exp_f32_e32 v232, v129
	v_sub_f32_e32 v129, v150, v123
	v_exp_f32_e32 v233, v129
	v_sub_f32_e32 v129, v152, v123
	v_add_f32_e32 v128, 0, v240
	v_exp_f32_e32 v236, v129
	v_sub_f32_e32 v129, v158, v123
	v_add_f32_e32 v128, v241, v128
	v_exp_f32_e32 v237, v129
	v_sub_f32_e32 v129, v151, v123
	v_add_f32_e32 v128, v232, v128
	v_exp_f32_e32 v238, v129
	v_sub_f32_e32 v129, v159, v123
	v_add_f32_e32 v128, v233, v128
	v_exp_f32_e32 v239, v129
	v_sub_f32_e32 v129, v161, v123
	v_add_f32_e32 v128, v236, v128
	v_exp_f32_e32 v228, v129
	v_sub_f32_e32 v129, v162, v123
	v_add_f32_e32 v128, v237, v128
	v_exp_f32_e32 v229, v129
	v_sub_f32_e32 v129, v160, v123
	v_add_f32_e32 v128, v238, v128
	v_exp_f32_e32 v226, v129
	v_sub_f32_e32 v129, v163, v123
	v_add_f32_e32 v128, v239, v128
	v_exp_f32_e32 v227, v129
	v_sub_f32_e32 v124, v124, v123
	v_add_f32_e32 v128, v228, v128
	v_exp_f32_e32 v230, v124
	v_sub_f32_e32 v125, v125, v123
	v_add_f32_e32 v128, v229, v128
	v_exp_f32_e32 v231, v125
	v_sub_f32_e32 v125, v126, v123
	v_add_f32_e32 v128, v226, v128
	v_exp_f32_e32 v234, v125
	v_sub_f32_e32 v123, v127, v123
	v_add_f32_e32 v128, v227, v128
	v_exp_f32_e32 v235, v123
	v_add_f32_e32 v124, v230, v128
	v_add_f32_e32 v124, v231, v124
	v_add_f32_e32 v124, v234, v124
	v_add_f32_e32 v151, v235, v124
	s_cbranch_execnz .LBB0_181
	s_branch .LBB0_180

.LBB0_180:
	v_add_u32_e32 v123, v122, v199
	ds_read_b128 v[124:127], v123
	ds_read_b128 v[154:157], v123 offset:64
	ds_read_b128 v[158:161], v123 offset:2304
	ds_read_b128 v[162:165], v123 offset:2368
	ds_read_b128 v[166:169], v123 offset:4608
	ds_read_b128 v[226:229], v123 offset:4672
	s_waitcnt lgkmcnt(5)
	v_mfma_f32_16x16x32_bf16 v[124:127], v[124:127], v[34:37], 0
	v_subrev_u32_e32 v233, 33, v153
	v_cvt_f32_u32_e32 v139, v233
	v_subrev_u32_e32 v235, 34, v153
	s_waitcnt lgkmcnt(3)
	v_mfma_f32_16x16x32_bf16 v[158:161], v[158:161], v[34:37], 0
	v_subrev_u32_e32 v236, 35, v153
	v_subrev_u32_e32 v237, 48, v153
	v_subrev_u32_e32 v238, 49, v153
	v_mfma_f32_16x16x32_bf16 v[124:127], v[154:157], v[38:41], v[124:127]
	v_subrev_u32_e32 v152, 17, v221
	v_subrev_u32_e32 v240, 50, v153
	v_subrev_u32_e32 v241, 51, v153
	s_waitcnt lgkmcnt(1)
	v_mfma_f32_16x16x32_bf16 v[154:157], v[166:169], v[34:37], 0
	ds_read_b128 v[166:169], v123 offset:6976
	v_add_u32_e32 v225, -3, v153
	v_add_u32_e32 v230, -2, v153
	v_mfma_f32_16x16x32_bf16 v[158:161], v[162:165], v[38:41], v[158:161]
	ds_read_b128 v[162:165], v123 offset:6912
	s_mov_b32 s0, 0x3e38aa3b
	v_cmp_gt_u32_e32 vcc, s81, v152
	s_waitcnt lgkmcnt(2)
	v_mfma_f32_16x16x32_bf16 v[154:157], v[226:229], v[38:41], v[154:157]
	v_cvt_f32_u32_e32 v226, v153
	v_cvt_f32_u32_e32 v227, v152
	v_add_u32_e32 v231, -16, v153
	s_waitcnt lgkmcnt(0)
	v_mfma_f32_16x16x32_bf16 v[162:165], v[162:165], v[34:37], 0
	v_mul_f32_e64 v226, v146, v226
	v_mul_f32_e64 v227, v147, v227
	s_nop 0
	v_mov_b32_e32 v144, v155
	v_pk_mul_f32 v[128:129], v[144:145], v[138:139]
	v_cvt_f32_u32_e32 v139, v235
	v_mov_b32_e32 v144, v156
	v_mfma_f32_16x16x32_bf16 v[162:165], v[166:169], v[38:41], v[162:165]
	v_fma_f32 v124, v124, s0, -v226
	v_fma_f32 v125, v125, s0, -v227
	v_pk_mul_f32 v[150:151], v[144:145], v[138:139]
	v_cvt_f32_u32_e32 v139, v236
	v_mov_b32_e32 v144, v157
	v_cvt_f32_u32_e32 v227, v225
	v_cvt_f32_u32_e32 v226, v230
	v_pk_mul_f32 v[156:157], v[144:145], v[138:139]
	v_cvt_f32_u32_e32 v139, v237
	v_mov_b32_e32 v144, v162
	v_subrev_u32_e32 v232, 17, v153
	v_subrev_u32_e32 v234, 19, v153
	v_pk_mul_f32 v[166:167], v[144:145], v[138:139]
	v_cvt_f32_u32_e32 v139, v238
	v_mov_b32_e32 v144, v163
	v_subrev_u32_e32 v123, 18, v153
	v_subrev_u32_e32 v239, 32, v153
	v_pk_mul_f32 v[162:163], v[144:145], v[138:139]
	v_cvt_f32_u32_e32 v139, v240
	v_mov_b32_e32 v144, v164
	v_cvt_f32_u32_e32 v155, v239
	v_mul_f32_e32 v154, 0x3e38aa3b, v154
	v_pk_mul_f32 v[168:169], v[144:145], v[138:139]
	v_cvt_f32_u32_e32 v139, v241
	v_mov_b32_e32 v144, v165
	v_mul_f32_e32 v164, v145, v155
	v_mov_b32_e32 v155, v128
	v_pk_mul_f32 v[228:229], v[144:145], v[138:139]
	v_cndmask_b32_e32 v139, v183, v125, vcc
	v_cmp_gt_u32_e32 vcc, s81, v153
	v_mov_b32_e32 v165, v129
	s_nop 0
	v_cndmask_b32_e32 v144, v183, v124, vcc
	v_pk_mul_f32 v[124:125], v[146:147], v[226:227]
	v_cmp_gt_u32_e32 vcc, s81, v225
	v_pk_fma_f32 v[124:125], v[126:127], s[0:1], v[124:125] op_sel_hi:[1,0,1] neg_lo:[0,0,1] neg_hi:[0,0,1]
	v_cvt_f32_u32_e32 v126, v231
	v_cvt_f32_u32_e32 v127, v232
	v_cndmask_b32_e32 v226, v183, v125, vcc
	v_cmp_gt_u32_e32 vcc, s81, v230
	v_max3_f32 v152, v144, s85, v139
	s_nop 0
	v_cndmask_b32_e32 v227, v183, v124, vcc
	v_pk_mul_f32 v[124:125], v[146:147], v[126:127]
	v_cvt_f32_u32_e32 v127, v234
	v_cvt_f32_u32_e32 v126, v123
	v_pk_fma_f32 v[124:125], v[158:159], s[0:1], v[124:125] op_sel_hi:[1,0,1] neg_lo:[0,0,1] neg_hi:[0,0,1]
	v_cmp_gt_u32_e32 vcc, s81, v232
	v_max3_f32 v152, v152, v227, v226
	s_nop 0
	v_cndmask_b32_e32 v158, v183, v125, vcc
	v_cmp_gt_u32_e32 vcc, s81, v231
	s_nop 1
	v_cndmask_b32_e32 v159, v183, v124, vcc
	v_pk_mul_f32 v[124:125], v[146:147], v[126:127]
	v_cmp_gt_u32_e32 vcc, s81, v234
	v_pk_fma_f32 v[124:125], v[160:161], s[0:1], v[124:125] op_sel_hi:[1,0,1] neg_lo:[0,0,1] neg_hi:[0,0,1]
	v_max3_f32 v152, v152, v159, v158
	v_cndmask_b32_e32 v126, v183, v125, vcc
	v_cmp_gt_u32_e32 vcc, s81, v123
	s_nop 1
	v_cndmask_b32_e32 v123, v183, v124, vcc
	v_pk_add_f32 v[124:125], v[154:155], v[164:165] neg_lo:[0,1] neg_hi:[0,1]
	v_cmp_gt_u32_e32 vcc, s81, v233
	v_max3_f32 v127, v152, v123, v126
	s_nop 0
	v_cndmask_b32_e32 v128, v183, v125, vcc
	v_cmp_gt_u32_e32 vcc, s81, v239
	v_mov_b32_e32 v125, v156
	v_mov_b32_e32 v156, v151
	v_cndmask_b32_e32 v129, v183, v124, vcc
	v_mov_b32_e32 v124, v150
	v_pk_add_f32 v[124:125], v[124:125], v[156:157] neg_lo:[0,1] neg_hi:[0,1]
	v_cmp_gt_u32_e32 vcc, s81, v236
	v_max3_f32 v127, v127, v129, v128
	s_nop 0
	v_cndmask_b32_e32 v150, v183, v125, vcc
	v_cmp_gt_u32_e32 vcc, s81, v235
	v_mov_b32_e32 v125, v162
	v_mov_b32_e32 v162, v167
	v_cndmask_b32_e32 v151, v183, v124, vcc
	v_mov_b32_e32 v124, v166
	v_pk_add_f32 v[124:125], v[124:125], v[162:163] neg_lo:[0,1] neg_hi:[0,1]
	v_cmp_gt_u32_e32 vcc, s81, v238
	v_max3_f32 v127, v127, v151, v150
	s_nop 0
	v_cndmask_b32_e32 v152, v183, v125, vcc
	v_cmp_gt_u32_e32 vcc, s81, v237
	v_mov_b32_e32 v125, v228
	v_mov_b32_e32 v228, v169
	v_cndmask_b32_e32 v154, v183, v124, vcc
	v_mov_b32_e32 v124, v168
	v_pk_add_f32 v[124:125], v[124:125], v[228:229] neg_lo:[0,1] neg_hi:[0,1]
	v_cmp_gt_u32_e32 vcc, s81, v241
	v_max3_f32 v127, v127, v154, v152
	s_nop 0
	v_cndmask_b32_e32 v125, v183, v125, vcc
	v_cmp_gt_u32_e32 vcc, s81, v240
	s_nop 1
	v_cndmask_b32_e32 v124, v183, v124, vcc
	v_max3_f32 v127, v127, v124, v125
	v_mov_b32_e32 v155, v127
	s_nop 1
	v_permlane16_swap_b32_e32 v127, v155
	v_cmp_lt_f32_e32 vcc, s39, v139
	s_waitcnt lgkmcnt(0)
	v_max_f32_e32 v127, v127, v155
	v_mov_b32_e32 v155, v127
	s_nop 1
	v_permlane32_swap_b32_e32 v127, v155
	s_waitcnt lgkmcnt(0)
	v_max3_f32 v225, v32, v127, v155
	v_sub_f32_e32 v127, v139, v225
	v_exp_f32_e32 v127, v127
	v_sub_f32_e32 v155, v144, v225
	v_exp_f32_e32 v155, v155
	v_sub_f32_e32 v139, v226, v225
	v_cndmask_b32_e32 v241, 0, v127, vcc
	v_cmp_lt_f32_e32 vcc, s39, v144
	v_exp_f32_e32 v139, v139
	v_sub_f32_e32 v144, v227, v225
	v_exp_f32_e32 v144, v144
	v_cndmask_b32_e32 v240, 0, v155, vcc
	v_cmp_lt_f32_e32 vcc, s39, v226
	v_add_f32_e32 v127, 0, v240
	v_add_f32_e32 v127, v241, v127
	v_cndmask_b32_e32 v233, 0, v139, vcc
	v_cmp_lt_f32_e32 vcc, s39, v227
	v_sub_f32_e32 v139, v158, v225
	v_exp_f32_e32 v139, v139
	v_cndmask_b32_e32 v232, 0, v144, vcc
	v_sub_f32_e32 v144, v159, v225
	v_exp_f32_e32 v144, v144
	v_cmp_lt_f32_e32 vcc, s39, v158
	v_add_f32_e32 v127, v232, v127
	v_add_f32_e32 v127, v233, v127
	v_cndmask_b32_e32 v237, 0, v139, vcc
	v_cmp_lt_f32_e32 vcc, s39, v159
	v_sub_f32_e32 v139, v126, v225
	v_exp_f32_e32 v139, v139
	v_cndmask_b32_e32 v236, 0, v144, vcc
	v_sub_f32_e32 v144, v123, v225
	v_exp_f32_e32 v144, v144
	v_cmp_lt_f32_e32 vcc, s39, v126
	v_add_f32_e32 v127, v236, v127
	v_add_f32_e32 v127, v237, v127
	v_cndmask_b32_e32 v239, 0, v139, vcc
	v_cmp_lt_f32_e32 vcc, s39, v123
	v_sub_f32_e32 v126, v128, v225
	v_exp_f32_e32 v126, v126
	v_cndmask_b32_e32 v238, 0, v144, vcc
	v_add_f32_e32 v123, v238, v127
	v_sub_f32_e32 v127, v129, v225
	v_exp_f32_e32 v127, v127
	v_cmp_lt_f32_e32 vcc, s39, v128
	v_add_f32_e32 v123, v239, v123
	s_nop 0
	v_cndmask_b32_e32 v229, 0, v126, vcc
	v_cmp_lt_f32_e32 vcc, s39, v129
	v_sub_f32_e32 v126, v150, v225
	v_exp_f32_e32 v126, v126
	v_cndmask_b32_e32 v228, 0, v127, vcc
	v_sub_f32_e32 v127, v151, v225
	v_exp_f32_e32 v127, v127
	v_cmp_lt_f32_e32 vcc, s39, v150
	v_add_f32_e32 v123, v228, v123
	v_add_f32_e32 v123, v229, v123
	v_cndmask_b32_e32 v227, 0, v126, vcc
	v_cmp_lt_f32_e32 vcc, s39, v151
	v_sub_f32_e32 v126, v152, v225
	v_exp_f32_e32 v126, v126
	v_cndmask_b32_e32 v226, 0, v127, vcc
	v_sub_f32_e32 v127, v154, v225
	v_exp_f32_e32 v127, v127
	v_cmp_lt_f32_e32 vcc, s39, v152
	v_add_f32_e32 v123, v226, v123
	v_add_f32_e32 v123, v227, v123
	v_cndmask_b32_e32 v231, 0, v126, vcc
	v_cmp_lt_f32_e32 vcc, s39, v154
	v_sub_f32_e32 v126, v125, v225
	v_exp_f32_e32 v126, v126
	v_cndmask_b32_e32 v230, 0, v127, vcc
	v_sub_f32_e32 v127, v124, v225
	v_exp_f32_e32 v127, v127
	v_cmp_lt_f32_e32 vcc, s39, v125
	v_add_f32_e32 v123, v230, v123
	v_add_f32_e32 v123, v231, v123
	v_cndmask_b32_e32 v235, 0, v126, vcc
	v_cmp_lt_f32_e32 vcc, s39, v124
	s_nop 1
	v_cndmask_b32_e32 v234, 0, v127, vcc
	v_add_f32_e32 v123, v234, v123
	v_add_f32_e32 v151, v235, v123
.LBB0_181:
	s_andn2_b64 vcc, exec, s[6:7]
	s_mov_b64 s[6:7], -1
	s_cbranch_vccnz .LBB0_183
	v_add_u32_e32 v123, v122, v199
	ds_read_b128 v[124:127], v123
	ds_read_b128 v[154:157], v123 offset:64
	v_cvt_f32_i32_e32 v128, v221
	s_waitcnt lgkmcnt(1)
	v_mfma_f32_16x16x32_bf16 v[124:127], v[124:127], v[42:45], 0
	s_waitcnt lgkmcnt(0)
	v_mfma_f32_16x16x32_bf16 v[124:127], v[154:157], v[46:49], v[124:127]
	ds_read_b128 v[154:157], v123 offset:2368
	s_nop 6
	v_fmamk_f32 v129, v124, 0x3e38aa3b, v137
	v_fmamk_f32 v139, v125, 0x3e38aa3b, v145
	v_max3_f32 v124, v129, s85, v139
	v_fmamk_f32 v144, v126, 0x3e38aa3b, v200
	v_fmamk_f32 v150, v127, 0x3e38aa3b, v201
	v_max3_f32 v152, v124, v144, v150
	ds_read_b128 v[124:127], v123 offset:2304
	s_waitcnt lgkmcnt(0)
	v_mfma_f32_16x16x32_bf16 v[124:127], v[124:127], v[42:45], 0
	v_mfma_f32_16x16x32_bf16 v[124:127], v[154:157], v[46:49], v[124:127]
	ds_read_b128 v[154:157], v123 offset:4672
	s_nop 6
	v_fmamk_f32 v158, v124, 0x3e38aa3b, v202
	v_fmamk_f32 v159, v125, 0x3e38aa3b, v203
	v_max3_f32 v124, v152, v158, v159
	v_fmamk_f32 v160, v126, 0x3e38aa3b, v204
	v_fmamk_f32 v161, v127, 0x3e38aa3b, v205
	v_max3_f32 v152, v124, v160, v161
	ds_read_b128 v[124:127], v123 offset:4608
	s_waitcnt lgkmcnt(0)
	v_mfma_f32_16x16x32_bf16 v[124:127], v[124:127], v[42:45], 0
	v_mfma_f32_16x16x32_bf16 v[124:127], v[154:157], v[46:49], v[124:127]
	ds_read_b128 v[154:157], v123 offset:6976
	s_nop 6
	v_fmamk_f32 v162, v124, 0x3e38aa3b, v206
	v_fmamk_f32 v163, v125, 0x3e38aa3b, v207
	v_max3_f32 v124, v152, v162, v163
	v_fmamk_f32 v164, v126, 0x3e38aa3b, v208
	v_fmamk_f32 v165, v127, 0x3e38aa3b, v209
	v_max3_f32 v152, v124, v164, v165
	ds_read_b128 v[124:127], v123 offset:6912
	s_waitcnt lgkmcnt(0)
	v_mfma_f32_16x16x32_bf16 v[124:127], v[124:127], v[42:45], 0
	v_mfma_f32_16x16x32_bf16 v[124:127], v[154:157], v[46:49], v[124:127]
	s_nop 7
	v_fmamk_f32 v157, v124, 0x3e38aa3b, v210
	v_fmamk_f32 v166, v125, 0x3e38aa3b, v211
	v_max3_f32 v123, v152, v157, v166
	v_fmamk_f32 v167, v126, 0x3e38aa3b, v212
	v_fmamk_f32 v168, v127, 0x3e38aa3b, v213
	v_max3_f32 v123, v123, v167, v168
	v_fma_f32 v123, -v145, v128, v123
	v_mov_b32_e32 v124, v123
	s_nop 1
	v_permlane16_swap_b32_e32 v123, v124
	s_waitcnt lgkmcnt(0)
	v_max_f32_e32 v123, v123, v124
	v_mov_b32_e32 v124, v123
	s_nop 1
	v_permlane32_swap_b32_e32 v123, v124
	s_waitcnt lgkmcnt(0)
	v_max3_f32 v123, v224, v123, v124
	v_fma_f32 v169, v145, v128, v123
	v_sub_f32_e32 v124, v129, v169
	v_exp_f32_e32 v124, v124
	v_sub_f32_e32 v125, v139, v169
	v_exp_f32_e32 v125, v125
	v_sub_f32_e32 v127, v144, v169
	v_exp_f32_e32 v127, v127
	v_sub_f32_e32 v128, v150, v169
	v_exp_f32_e32 v129, v128
	v_sub_f32_e32 v128, v158, v169
	v_add_f32_e32 v126, 0, v124
	v_exp_f32_e32 v152, v128
	v_sub_f32_e32 v128, v159, v169
	v_add_f32_e32 v126, v125, v126
	v_exp_f32_e32 v154, v128
	v_sub_f32_e32 v128, v160, v169
	v_add_f32_e32 v126, v127, v126
	v_exp_f32_e32 v155, v128
	v_sub_f32_e32 v128, v161, v169
	v_add_f32_e32 v126, v129, v126
	v_exp_f32_e32 v156, v128
	v_add_f32_e32 v126, v152, v126
	v_add_f32_e32 v126, v154, v126
	v_add_f32_e32 v126, v155, v126
	v_add_f32_e32 v128, v156, v126
	v_sub_f32_e32 v126, v162, v169
	v_exp_f32_e32 v126, v126
	v_sub_f32_e32 v144, v164, v169
	v_exp_f32_e32 v144, v144
	v_sub_f32_e32 v157, v157, v169
	v_add_f32_e32 v139, v126, v128
	v_sub_f32_e32 v128, v163, v169
	v_exp_f32_e32 v128, v128
	v_exp_f32_e32 v157, v157
	v_sub_f32_e32 v158, v166, v169
	v_exp_f32_e32 v158, v158
	v_add_f32_e32 v139, v128, v139
	v_add_f32_e32 v150, v144, v139
	v_sub_f32_e32 v139, v165, v169
	v_exp_f32_e32 v139, v139
	v_sub_f32_e32 v159, v167, v169
	v_exp_f32_e32 v159, v159
	v_sub_f32_e32 v160, v168, v169
	v_add_f32_e32 v150, v139, v150
	v_exp_f32_e32 v160, v160
	v_add_f32_e32 v150, v157, v150
	v_add_f32_e32 v150, v158, v150
	v_add_f32_e32 v150, v159, v150
	v_add_f32_e32 v150, v160, v150
	s_cbranch_execz .LBB0_184
	s_branch .LBB0_185

.LBB0_184:
	v_add_u32_e32 v150, v122, v199
	ds_read_b128 v[122:125], v150
	ds_read_b128 v[126:129], v150 offset:64
	v_subrev_u32_e32 v249, 32, v221
	v_cvt_f32_u32_e32 v139, v249
	ds_read_b128 v[162:165], v150 offset:6912
	ds_read_b128 v[166:169], v150 offset:6976
	v_subrev_u32_e32 v251, 34, v221
	v_subrev_u32_e32 v250, 35, v221
	v_subrev_u32_e32 v181, 48, v221
	s_waitcnt lgkmcnt(3)
	v_mfma_f32_16x16x32_bf16 v[122:125], v[122:125], v[42:45], 0
	v_subrev_u32_e32 v192, 50, v221
	v_add_u32_e32 v242, -1, v221
	v_cmp_gt_u32_e64 s[6:7], s81, v242
	s_waitcnt lgkmcnt(2)
	v_mfma_f32_16x16x32_bf16 v[126:129], v[126:129], v[46:49], v[122:125]
	ds_read_b128 v[154:157], v150 offset:2368
	v_cvt_f32_u32_e32 v243, v242
	v_cvt_f32_u32_e32 v242, v221
	ds_read_b128 v[122:125], v150 offset:2304
	s_waitcnt lgkmcnt(3)
	v_mfma_f32_16x16x32_bf16 v[162:165], v[162:165], v[42:45], 0
	v_subrev_u32_e32 v184, 51, v221
	v_pk_mul_f32 v[242:243], v[146:147], v[242:243]
	s_mov_b32 s0, 0x3e38aa3b
	s_waitcnt lgkmcnt(0)
	v_mfma_f32_16x16x32_bf16 v[122:125], v[122:125], v[42:45], 0
	ds_read_b128 v[158:161], v150 offset:4672
	v_add_u32_e32 v244, -3, v221
	v_add_u32_e32 v245, -2, v221
	v_mfma_f32_16x16x32_bf16 v[122:125], v[154:157], v[46:49], v[122:125]
	ds_read_b128 v[154:157], v150 offset:4608
	v_subrev_u32_e32 v150, 49, v221
	v_cmp_gt_u32_e32 vcc, s81, v221
	v_mfma_f32_16x16x32_bf16 v[164:167], v[166:169], v[46:49], v[162:165]
	v_fma_f32 v126, v126, s0, -v242
	v_fma_f32 v127, v127, s0, -v243
	v_subrev_u32_e32 v246, 17, v221
	v_cmp_gt_u32_e64 s[42:43], s81, v244
	s_waitcnt lgkmcnt(0)
	v_mfma_f32_16x16x32_bf16 v[154:157], v[154:157], v[42:45], 0
	v_subrev_u32_e32 v247, 19, v221
	v_subrev_u32_e32 v248, 18, v221
	v_cmp_gt_u32_e64 s[46:47], s81, v246
	v_mfma_f32_16x16x32_bf16 v[156:159], v[158:161], v[46:49], v[154:157]
	v_cmp_gt_u32_e64 s[50:51], s81, v247
	v_cmp_gt_u32_e64 s[54:55], s81, v250
	v_cmp_gt_u32_e64 s[58:59], s81, v150
	s_nop 0
	v_subrev_u32_e32 v155, 33, v221
	v_mul_f32_e32 v154, v145, v139
	v_cvt_f32_u32_e32 v139, v155
	s_nop 0
	v_mov_b32_e32 v144, v157
	v_mul_f32_e32 v152, 0x3e38aa3b, v156
	v_cmp_gt_u32_e64 s[52:53], s81, v155
	v_pk_mul_f32 v[160:161], v[144:145], v[138:139]
	v_cvt_f32_u32_e32 v139, v251
	v_mov_b32_e32 v144, v158
	v_mov_b32_e32 v155, v161
	v_cmp_gt_u32_e64 s[66:67], s81, v184
	v_pk_mul_f32 v[156:157], v[144:145], v[138:139]
	v_cvt_f32_u32_e32 v139, v250
	v_mov_b32_e32 v144, v159
	v_pk_mul_f32 v[158:159], v[144:145], v[138:139]
	v_cvt_f32_u32_e32 v139, v181
	v_mov_b32_e32 v144, v164
	v_pk_mul_f32 v[162:163], v[144:145], v[138:139]
	v_cvt_f32_u32_e32 v139, v150
	v_mov_b32_e32 v144, v165
	v_pk_mul_f32 v[168:169], v[144:145], v[138:139]
	v_cvt_f32_u32_e32 v139, v192
	v_mov_b32_e32 v144, v166
	v_pk_mul_f32 v[164:165], v[144:145], v[138:139]
	v_cvt_f32_u32_e32 v139, v184
	v_mov_b32_e32 v144, v167
	v_pk_mul_f32 v[166:167], v[144:145], v[138:139]
	v_cndmask_b32_e64 v139, v183, v127, s[6:7]
	v_cndmask_b32_e32 v144, v183, v126, vcc
	v_cvt_f32_u32_e32 v127, v244
	v_cvt_f32_u32_e32 v126, v245
	v_cmp_gt_u32_e64 s[6:7], s81, v245
	v_max3_f32 v242, v144, s85, v139
	v_cmp_lt_f32_e32 vcc, s39, v144
	v_pk_mul_f32 v[126:127], v[146:147], v[126:127]
	v_cmp_lt_f32_e64 s[40:41], s39, v139
	v_pk_fma_f32 v[126:127], v[128:129], s[0:1], v[126:127] op_sel_hi:[1,0,1] neg_lo:[0,0,1] neg_hi:[0,0,1]
	s_nop 0
	v_cndmask_b32_e64 v128, v183, v127, s[42:43]
	v_cndmask_b32_e64 v129, v183, v126, s[6:7]
	v_cvt_f32_u32_e32 v126, v153
	v_cvt_f32_u32_e32 v127, v246
	v_cmp_gt_u32_e64 s[6:7], s81, v153
	v_max3_f32 v242, v242, v129, v128
	v_mov_b32_e32 v153, v160
	v_pk_mul_f32 v[126:127], v[146:147], v[126:127]
	v_cmp_lt_f32_e64 s[44:45], s39, v128
	v_pk_fma_f32 v[122:123], v[122:123], s[0:1], v[126:127] op_sel_hi:[1,0,1] neg_lo:[0,0,1] neg_hi:[0,0,1]
	v_cmp_lt_f32_e64 s[42:43], s39, v129
	v_cndmask_b32_e64 v126, v183, v123, s[46:47]
	v_cndmask_b32_e64 v243, v183, v122, s[6:7]
	v_cvt_f32_u32_e32 v123, v247
	v_cvt_f32_u32_e32 v122, v248
	v_cmp_gt_u32_e64 s[6:7], s81, v248
	v_max3_f32 v127, v242, v243, v126
	v_cmp_lt_f32_e64 s[48:49], s39, v126
	v_pk_mul_f32 v[122:123], v[146:147], v[122:123]
	v_cmp_lt_f32_e64 s[46:47], s39, v243
	v_pk_fma_f32 v[122:123], v[124:125], s[0:1], v[122:123] op_sel_hi:[1,0,1] neg_lo:[0,0,1] neg_hi:[0,0,1]
	s_nop 0
	v_cndmask_b32_e64 v242, v183, v123, s[50:51]
	v_cndmask_b32_e64 v244, v183, v122, s[6:7]
	v_cmp_gt_u32_e64 s[6:7], s81, v249
	v_pk_add_f32 v[122:123], v[152:153], v[154:155] neg_lo:[0,1] neg_hi:[0,1]
	v_max3_f32 v124, v127, v244, v242
	v_cndmask_b32_e64 v153, v183, v123, s[52:53]
	v_cndmask_b32_e64 v160, v183, v122, s[6:7]
	v_mov_b32_e32 v122, v156
	v_mov_b32_e32 v123, v158
	v_mov_b32_e32 v158, v157
	v_cmp_gt_u32_e64 s[6:7], s81, v251
	v_pk_add_f32 v[122:123], v[122:123], v[158:159] neg_lo:[0,1] neg_hi:[0,1]
	v_max3_f32 v124, v124, v160, v153
	v_cndmask_b32_e64 v157, v183, v123, s[54:55]
	v_cndmask_b32_e64 v158, v183, v122, s[6:7]
	v_mov_b32_e32 v122, v162
	v_mov_b32_e32 v123, v168
	v_mov_b32_e32 v168, v163
	v_cmp_gt_u32_e64 s[6:7], s81, v181
	v_pk_add_f32 v[122:123], v[122:123], v[168:169] neg_lo:[0,1] neg_hi:[0,1]
	v_max3_f32 v124, v124, v158, v157
	v_cndmask_b32_e64 v150, v183, v123, s[58:59]
	v_cndmask_b32_e64 v159, v183, v122, s[6:7]
	v_mov_b32_e32 v122, v164
	v_mov_b32_e32 v123, v166
	v_mov_b32_e32 v166, v165
	v_cmp_gt_u32_e64 s[6:7], s81, v192
	v_pk_add_f32 v[122:123], v[122:123], v[166:167] neg_lo:[0,1] neg_hi:[0,1]
	v_max3_f32 v124, v124, v159, v150
	v_cndmask_b32_e64 v161, v183, v123, s[66:67]
	v_cndmask_b32_e64 v122, v183, v122, s[6:7]
	v_max3_f32 v123, v124, v122, v161
	v_mov_b32_e32 v124, v123
	s_nop 1
	v_permlane16_swap_b32_e32 v123, v124
	v_cmp_lt_f32_e64 s[50:51], s39, v244
	v_cmp_lt_f32_e64 s[56:57], s39, v242
	v_cmp_lt_f32_e64 s[52:53], s39, v160
	v_cmp_lt_f32_e64 s[60:61], s39, v153
	s_waitcnt lgkmcnt(0)
	v_max_f32_e32 v123, v123, v124
	v_mov_b32_e32 v124, v123
	s_nop 1
	v_permlane32_swap_b32_e32 v123, v124
	v_cmp_lt_f32_e64 s[62:63], s39, v157
	v_cmp_lt_f32_e64 s[64:65], s39, v150
	v_cmp_lt_f32_e64 s[54:55], s39, v158
	v_cmp_lt_f32_e64 s[58:59], s39, v159
	s_waitcnt lgkmcnt(0)
	v_max3_f32 v123, v224, v123, v124
	v_sub_f32_e32 v124, v144, v123
	v_exp_f32_e32 v124, v124
	v_sub_f32_e32 v125, v139, v123
	v_exp_f32_e32 v125, v125
	v_sub_f32_e32 v128, v128, v123
	v_cndmask_b32_e32 v124, 0, v124, vcc
	v_add_f32_e32 v127, 0, v124
	v_cndmask_b32_e64 v125, 0, v125, s[40:41]
	v_add_f32_e32 v139, v125, v127
	v_sub_f32_e32 v127, v129, v123
	v_exp_f32_e32 v127, v127
	v_exp_f32_e32 v128, v128
	v_sub_f32_e32 v126, v126, v123
	v_exp_f32_e32 v126, v126
	v_cndmask_b32_e64 v127, 0, v127, s[42:43]
	v_cndmask_b32_e64 v129, 0, v128, s[44:45]
	v_add_f32_e32 v128, v127, v139
	v_sub_f32_e32 v139, v243, v123
	v_exp_f32_e32 v139, v139
	v_add_f32_e32 v128, v129, v128
	v_cndmask_b32_e64 v154, 0, v126, s[48:49]
	v_sub_f32_e32 v150, v150, v123
	v_cndmask_b32_e64 v152, 0, v139, s[46:47]
	v_add_f32_e32 v126, v152, v128
	v_sub_f32_e32 v128, v244, v123
	v_exp_f32_e32 v128, v128
	v_sub_f32_e32 v139, v242, v123
	v_exp_f32_e32 v139, v139
	v_add_f32_e32 v126, v154, v126
	v_cndmask_b32_e64 v155, 0, v128, s[50:51]
	v_add_f32_e32 v126, v155, v126
	v_cndmask_b32_e64 v156, 0, v139, s[56:57]
	v_add_f32_e32 v139, v156, v126
	v_sub_f32_e32 v126, v160, v123
	v_exp_f32_e32 v126, v126
	v_sub_f32_e32 v128, v153, v123
	v_exp_f32_e32 v128, v128
	v_exp_f32_e32 v150, v150
	v_cndmask_b32_e64 v126, 0, v126, s[52:53]
	v_add_f32_e32 v139, v126, v139
	v_cndmask_b32_e64 v128, 0, v128, s[60:61]
	v_add_f32_e32 v153, v128, v139
	v_sub_f32_e32 v139, v158, v123
	v_exp_f32_e32 v144, v139
	v_sub_f32_e32 v139, v157, v123
	v_exp_f32_e32 v139, v139
	v_sub_f32_e32 v157, v159, v123
	v_exp_f32_e32 v157, v157
	v_cndmask_b32_e64 v144, 0, v144, s[54:55]
	v_cndmask_b32_e64 v139, 0, v139, s[62:63]
	v_add_f32_e32 v153, v144, v153
	v_add_f32_e32 v153, v139, v153
	v_cndmask_b32_e64 v157, 0, v157, s[58:59]
	v_cndmask_b32_e64 v158, 0, v150, s[64:65]
	v_add_f32_e32 v150, v157, v153
	v_sub_f32_e32 v153, v122, v123
	v_exp_f32_e32 v153, v153
	v_cmp_lt_f32_e32 vcc, s39, v122
	v_sub_f32_e32 v122, v161, v123
	v_exp_f32_e32 v122, v122
	v_add_f32_e32 v150, v158, v150
	v_cmp_lt_f32_e64 s[6:7], s39, v161
	v_cndmask_b32_e32 v159, 0, v153, vcc
	v_readlane_b32 s62, v254, 53
	v_readlane_b32 s60, v254, 51
	v_cndmask_b32_e64 v160, 0, v122, s[6:7]
	v_add_f32_e32 v122, v159, v150
	v_readlane_b32 s63, v254, 54
	v_readlane_b32 s61, v254, 52
	v_add_f32_e32 v150, v160, v122
